# forget_logits load batching + attention gain-max loop batched + x-loop counted wait + mid-block setprio pairs removed
# speedup vs baseline: 1.0892x; 1.0033x over previous
; #define IN(i) karg_in(A, i)
; __device__ __forceinline__ void attention_phase(KArgs A, unsigned char* ldsg, int G) {
;     ...
;     float Bnd; { float gq = 0.f, gk = 0.f; for (int i = 0; i < HD; ++i) { gq = fmaxf(gq, fabsf(IN(11)[i])); gk = fmaxf(gk, fabsf(IN(12)[i])); } Bnd = 64.0f * attn_body::C2 * gq * gk * 1.03f + 0.5f; }
;     if (__builtin_amdgcn_readfirstlane((int)(threadIdx.x >> 6)) >= 4) __builtin_amdgcn_s_setprio(1);
.LBB0_20:
	s_waitcnt lgkmcnt(0)
	global_load_dwordx4 v[4:7], v1, s[44:45]
	global_load_dwordx4 v[8:11], v1, s[44:45] offset:16
	global_load_dwordx4 v[12:15], v1, s[44:45] offset:32
	global_load_dwordx4 v[16:19], v1, s[44:45] offset:48
	global_load_dwordx4 v[20:23], v1, s[44:45] offset:64
	global_load_dwordx4 v[24:27], v1, s[44:45] offset:80
	global_load_dwordx4 v[28:31], v1, s[44:45] offset:96
	global_load_dwordx4 v[32:35], v1, s[44:45] offset:112
	global_load_dwordx4 v[36:39], v1, s[44:45] offset:128
	global_load_dwordx4 v[40:43], v1, s[44:45] offset:144
	global_load_dwordx4 v[44:47], v1, s[44:45] offset:160
	global_load_dwordx4 v[48:51], v1, s[44:45] offset:176
	global_load_dwordx4 v[52:55], v1, s[44:45] offset:192
	global_load_dwordx4 v[56:59], v1, s[44:45] offset:208
	global_load_dwordx4 v[60:63], v1, s[44:45] offset:224
	global_load_dwordx4 v[64:67], v1, s[44:45] offset:240
	global_load_dwordx4 v[68:71], v1, s[46:47]
	global_load_dwordx4 v[72:75], v1, s[46:47] offset:16
	global_load_dwordx4 v[76:79], v1, s[46:47] offset:32
	global_load_dwordx4 v[80:83], v1, s[46:47] offset:48
	global_load_dwordx4 v[84:87], v1, s[46:47] offset:64
	global_load_dwordx4 v[88:91], v1, s[46:47] offset:80
	global_load_dwordx4 v[92:95], v1, s[46:47] offset:96
	global_load_dwordx4 v[96:99], v1, s[46:47] offset:112
	global_load_dwordx4 v[100:103], v1, s[46:47] offset:128
	global_load_dwordx4 v[104:107], v1, s[46:47] offset:144
	global_load_dwordx4 v[108:111], v1, s[46:47] offset:160
	global_load_dwordx4 v[112:115], v1, s[46:47] offset:176
	global_load_dwordx4 v[116:119], v1, s[46:47] offset:192
	global_load_dwordx4 v[120:123], v1, s[46:47] offset:208
	global_load_dwordx4 v[124:127], v1, s[46:47] offset:224
	global_load_dwordx4 v[128:131], v1, s[46:47] offset:240
	s_mov_b64 s[8:9], 0x100
	s_waitcnt vmcnt(0)
	v_max3_f32 v2, v2, |v4|, |v5|
	v_max3_f32 v2, v2, |v6|, |v7|
	v_max3_f32 v2, v2, |v8|, |v9|
	v_max3_f32 v2, v2, |v10|, |v11|
	v_max3_f32 v2, v2, |v12|, |v13|
	v_max3_f32 v2, v2, |v14|, |v15|
	v_max3_f32 v2, v2, |v16|, |v17|
	v_max3_f32 v2, v2, |v18|, |v19|
	v_max3_f32 v2, v2, |v20|, |v21|
	v_max3_f32 v2, v2, |v22|, |v23|
	v_max3_f32 v2, v2, |v24|, |v25|
	v_max3_f32 v2, v2, |v26|, |v27|
	v_max3_f32 v2, v2, |v28|, |v29|
	v_max3_f32 v2, v2, |v30|, |v31|
	v_max3_f32 v2, v2, |v32|, |v33|
	v_max3_f32 v2, v2, |v34|, |v35|
	v_max3_f32 v2, v2, |v36|, |v37|
	v_max3_f32 v2, v2, |v38|, |v39|
	v_max3_f32 v2, v2, |v40|, |v41|
	v_max3_f32 v2, v2, |v42|, |v43|
	v_max3_f32 v2, v2, |v44|, |v45|
	v_max3_f32 v2, v2, |v46|, |v47|
	v_max3_f32 v2, v2, |v48|, |v49|
	v_max3_f32 v2, v2, |v50|, |v51|
	v_max3_f32 v2, v2, |v52|, |v53|
	v_max3_f32 v2, v2, |v54|, |v55|
	v_max3_f32 v2, v2, |v56|, |v57|
	v_max3_f32 v2, v2, |v58|, |v59|
	v_max3_f32 v2, v2, |v60|, |v61|
	v_max3_f32 v2, v2, |v62|, |v63|
	v_max3_f32 v2, v2, |v64|, |v65|
	v_max3_f32 v2, v2, |v66|, |v67|
	v_max3_f32 v0, v0, |v68|, |v69|
	v_max3_f32 v0, v0, |v70|, |v71|
	v_max3_f32 v0, v0, |v72|, |v73|
	v_max3_f32 v0, v0, |v74|, |v75|
	v_max3_f32 v0, v0, |v76|, |v77|
	v_max3_f32 v0, v0, |v78|, |v79|
	v_max3_f32 v0, v0, |v80|, |v81|
	v_max3_f32 v0, v0, |v82|, |v83|
	v_max3_f32 v0, v0, |v84|, |v85|
	v_max3_f32 v0, v0, |v86|, |v87|
	v_max3_f32 v0, v0, |v88|, |v89|
	v_max3_f32 v0, v0, |v90|, |v91|
	v_max3_f32 v0, v0, |v92|, |v93|
	v_max3_f32 v0, v0, |v94|, |v95|
	v_max3_f32 v0, v0, |v96|, |v97|
	v_max3_f32 v0, v0, |v98|, |v99|
	v_max3_f32 v0, v0, |v100|, |v101|
	v_max3_f32 v0, v0, |v102|, |v103|
	v_max3_f32 v0, v0, |v104|, |v105|
	v_max3_f32 v0, v0, |v106|, |v107|
	v_max3_f32 v0, v0, |v108|, |v109|
	v_max3_f32 v0, v0, |v110|, |v111|
	v_max3_f32 v0, v0, |v112|, |v113|
	v_max3_f32 v0, v0, |v114|, |v115|
	v_max3_f32 v0, v0, |v116|, |v117|
	v_max3_f32 v0, v0, |v118|, |v119|
	v_max3_f32 v0, v0, |v120|, |v121|
	v_max3_f32 v0, v0, |v122|, |v123|
	v_max3_f32 v0, v0, |v124|, |v125|
	v_max3_f32 v0, v0, |v126|, |v127|
	v_max3_f32 v0, v0, |v128|, |v129|
	v_max3_f32 v0, v0, |v130|, |v131|
	v_readfirstlane_b32 s4, v230
	s_cmpk_gt_u32 s4, 0xff
	s_cbranch_scc0 .LBB0_23
	s_setprio 1
